# layer-1 weight conversion moved out of the first phase into the idle tails of the layer-0 in-proj and up GEMM phases (own copy of the item loop per call site, drained at the layer-0 down phase)
# speedup vs baseline: 1.0636x; 1.0083x over previous
; #define LAS __attribute__((address_space(3)))
; DI unsigned xb_add(unsigned* p, unsigned v) { return __hip_atomic_fetch_add(p, v, __ATOMIC_RELAXED, __HIP_MEMORY_SCOPE_AGENT); }
; DI unsigned xb_xcc_id() { return (unsigned)__builtin_amdgcn_s_getreg((3 << 11) | 20) & 0xFu; }
; DI XcdBarrier xcd_barrier_post(unsigned* bar, volatile LAS unsigned* st) {
;     XcdBarrier b; b.bar = bar; b.x = xb_xcc_id(); b.st = st;
;     if (threadIdx.x == 0) (void)xb_add(&bar[XB_XCNT(b.x)], 1u);
;     return b;
; __global__ void __launch_bounds__(512, 2) fwd_kernel(Params p) {
;     extern __shared__ __attribute__((aligned(16))) unsigned char smem[];
;     LAS unsigned char* lds = (LAS unsigned char*)smem;
;     cg::grid_group grid = cg::this_grid();
;     if (threadIdx.x < 32) ((volatile LAS unsigned*)(lds + LDS_CTRL))[threadIdx.x] = 0u;
;     __syncthreads();
;     const XcdBarrier bar = xcd_barrier_post((unsigned*)(p.ws + WS_CTL), (volatile LAS unsigned*)(lds + LDS_CTRL));
_Z10fwd_kernel6Params:
	v_writelane_b32 v255, s0, 62
	v_writelane_b32 v255, s1, 63
	s_load_dwordx16 s[36:51], s[0:1], 0x80
	s_load_dword s33, s[0:1], 0xc8
	s_mov_b32 s26, s2
	s_add_u32 s2, s0, 0xc8
	v_and_b32_e32 v202, 0x3ff, v0
	s_addc_u32 s3, s1, 0
	v_cmp_gt_u32_e32 vcc, 32, v202
	s_and_saveexec_b64 s[4:5], vcc
	v_lshl_add_u32 v1, v202, 2, 0
	v_add_u32_e32 v1, 0x22000, v1
	v_mov_b32_e32 v2, 0
	ds_write_b32 v1, v2
	s_or_b64 exec, exec, s[4:5]
	s_load_dword s8, s[0:1], 0xc0
	s_waitcnt lgkmcnt(0)
	s_barrier
	s_getreg_b32 s4, hwreg(HW_REG_XCC_ID, 0, 4)
	s_and_b32 s4, s4, 15
	v_cmp_eq_u32_e64 s[24:25], 0, v202
	v_writelane_b32 v253, s4, 0
	s_and_saveexec_b64 s[4:5], s[24:25]
	s_cbranch_execz .LBB0_5
	s_mov_b64 s[6:7], exec
	v_mbcnt_lo_u32_b32 v1, s6, 0
	v_mbcnt_hi_u32_b32 v1, s7, v1
	v_cmp_eq_u32_e32 vcc, 0, v1
	s_and_b64 s[10:11], exec, vcc
	s_mov_b64 exec, s[10:11]
	s_cbranch_execz .LBB0_5
	v_readlane_b32 s9, v253, 0
	s_lshl_b32 s9, s9, 8
	s_bcnt1_i32_b64 s6, s[6:7]
	v_mov_b32_e32 v1, s9
	v_mov_b32_e32 v2, s6
	global_atomic_add v1, v2, s[50:51] offset:1024

; #define LAS __attribute__((address_space(3)))
; DI int otid() { int t = threadIdx.x; asm volatile("" : "+v"(t)); return t; }
; DI void prep_items(const Params& p, LAS unsigned char* lds, int l, unsigned* ctr, int max_items) {
;     const int tid = otid(), lane = tid & 63, wid = tid >> 6;
;     LAS float* s_c = (LAS float*)lds;
;     LAS float* s_red = (LAS float*)(lds + 40960);
;     volatile LAS int* slot = (volatile LAS int*)(lds + LDS_CTRL + 64);
;     constexpr int N_ADA = 48, PER_L = 12832, N_CONV = PER_L / 8;
;     const int n_tab = (l == 0) ? 48 : 0;
;     float* mod = (float*)(p.ws + WS_MOD);
;     bool have_c = false;
;     for (int done = 0; done < max_items; ++done) {
;         const int it = next_item(ctr, slot);
;         if (it >= N_ADA + n_tab + N_CONV) break;
; DI void phase_prep(const Params& p, LAS unsigned char* lds) { prep_items(p, lds, 0, (unsigned*)(p.ws + WS_QCTR), 1 << 30); prep_items(p, lds, 1, (unsigned*)(p.ws + WS_QCTR + 256 * 5), 1 << 30); }
.LBB0_17:
	s_add_u32 s20, s50, 0x4000
	s_addc_u32 s21, s51, 0
	s_add_u32 s14, s50, 0x8000
	s_addc_u32 s15, s51, 0
	s_add_u32 s0, s50, 0x9fa0000
	s_addc_u32 s1, s51, 0
	v_writelane_b32 v253, s0, 1
	v_mov_b32_e32 v68, v202
	s_movk_i32 s30, 0x1400
	v_writelane_b32 v253, s1, 2
	s_add_u32 s0, s50, 0x47a0000
	s_addc_u32 s1, s51, 0
	v_writelane_b32 v253, s0, 3
	v_and_b32_e32 v0, 63, v68
	v_lshlrev_b32_e32 v83, 2, v0
	v_writelane_b32 v253, s1, 4
	s_add_u32 s0, s50, 0x37a0000
	s_addc_u32 s1, s51, 0
	v_writelane_b32 v253, s0, 5
	v_lshlrev_b32_e32 v2, 1, v68
	v_and_b32_e32 v1, 28, v83
	v_writelane_b32 v253, s1, 6
	s_add_u32 s0, s50, 0x3520000
	s_addc_u32 s1, s51, 0
	v_writelane_b32 v253, s0, 7
	s_waitcnt lgkmcnt(0)
	s_cmp_lg_u64 s[52:53], 0
	v_and_b32_e32 v2, 16, v2
	v_writelane_b32 v253, s1, 8
	s_cselect_b64 s[0:1], -1, 0
	v_writelane_b32 v253, s0, 9
	v_or_b32_e32 v3, v2, v1
	v_add3_u32 v2, v1, v2, 16
	v_writelane_b32 v253, s1, 10
	s_add_u32 s0, s50, 0x3320000
	s_addc_u32 s1, s51, 0
	v_writelane_b32 v253, s0, 11
	s_cmp_lg_u64 s[82:83], 0
	v_cmp_gt_u32_e32 vcc, 16, v1
	v_writelane_b32 v253, s1, 12
	s_cselect_b64 s[0:1], -1, 0
	v_cndmask_b32_e32 v87, v2, v3, vcc
	v_lshlrev_b32_e32 v1, 3, v68
	v_lshlrev_b32_e32 v2, 4, v0
	v_mov_b32_e32 v0, 2
	v_writelane_b32 v253, s0, 13
	v_ashrrev_i32_e32 v82, 6, v68
	v_add_u32_e32 v88, 0xfffd0000, v1
	v_and_b32_e32 v90, 56, v1
	v_and_b32_e32 v91, 24, v1
	v_lshlrev_b32_sdwa v0, v0, v68 dst_sel:DWORD dst_unused:UNUSED_PAD src0_sel:DWORD src1_sel:BYTE_0
	v_mov_b32_e32 v1, 0
	v_writelane_b32 v253, s1, 14
	s_add_u32 s0, s50, 0x320000
	v_add_u32_e32 v92, 0, v0
	v_lshl_add_u64 v[70:71], s[14:15], 0, v[0:1]
	s_addc_u32 s1, s51, 0
	v_max_i32_e32 v0, 0x7f8, v82
	v_writelane_b32 v253, s0, 15
	v_sub_u32_e32 v0, v0, v82
	s_mov_b32 s27, 0xc000
	s_movk_i32 s2, 0x2800
	v_mul_lo_u32 v3, v82, s30
	v_writelane_b32 v253, s1, 16
	s_add_u32 s88, s50, 0x100000
	v_add_u32_e32 v0, 7, v0
	v_mad_i64_i32 v[4:5], s[0:1], v82, s27, 0
	v_add3_u32 v89, 0, v3, v2
	s_addc_u32 s89, s51, 0
	v_lshrrev_b32_e32 v3, 3, v0
	v_cmp_gt_i32_e64 s[0:1], s2, v68
	s_add_u32 s90, s50, 0x80000
	v_add_u32_e32 v3, 1, v3
	v_writelane_b32 v253, s0, 17
	s_addc_u32 s91, s51, 0
	v_and_b32_e32 v6, 7, v3
	v_and_b32_e32 v7, 56, v0
	v_ashrrev_i32_e32 v69, 31, v68
	v_mov_b32_e32 v3, v1
	v_or_b32_e32 v4, v4, v2
	s_add_i32 s34, 0, 0x22040
	v_writelane_b32 v253, s1, 18
	s_movk_i32 s0, 0x800
	s_movk_i32 s31, 0x500
	v_and_b32_e32 v84, 0x7c, v83
	v_or_b32_e32 v85, 0xffff9c00, v83
	v_or_b32_e32 v86, 0xffffa000, v83
	v_add_u32_e32 v93, 0xfffffd00, v82
	v_lshl_add_u32 v94, v68, 2, 0
	v_lshl_add_u64 v[72:73], v[68:69], 2, s[70:71]
	v_lshl_add_u32 v69, v82, 2, 0
	v_lshl_add_u64 v[74:75], s[76:77], 0, v[4:5]
	v_sub_u32_e32 v95, 0, v6
	v_lshl_add_u64 v[76:77], s[76:77], 0, v[2:3]
	v_mov_b32_e32 v96, s34
	v_mov_b32_e32 v97, 0xffffea00
	v_mov_b32_e32 v98, 0x80
	v_mov_b32_e32 v99, 0x42800000
	v_not_b32_e32 v100, 63
	v_cmp_gt_i32_e64 s[4:5], s0, v82
	s_mov_b32 s35, 0
	s_movk_i32 s84, 0x2000
	s_mov_b32 s85, 0xffff
	s_mov_b32 s86, 0xc1549a78
	s_mov_b32 s87, 0xc2fc0000
	v_cmp_gt_i32_e64 s[6:7], s31, v68
	s_mov_b64 s[94:95], 0
	v_cmp_ne_u32_e64 s[8:9], 56, v7
	v_cmp_lt_u32_e64 s[10:11], 55, v0
	s_mov_b64 s[92:93], 0x300000
	s_sub_u32 s0, s26, 48
	s_cmp_lt_u32 s0, 48
	s_cbranch_scc1 .LBB0_235
	s_branch .LBB0_21

; DI void prep_items(const Params& p, LAS unsigned char* lds, int l, unsigned* ctr, int max_items) {
;     ...
;     for (int done = 0; done < max_items; ++done) {
;         const int it = next_item(ctr, slot);
;         if (it >= N_ADA + n_tab + N_CONV) break;
;     ...
;             int id = (it - N_ADA - n_tab) * 8 + wid;
;             if (id < 3072) conv_witem(p.in[6] + (size_t)l * 2048 * INW, 2048, INW, (bf16_t*)(p.ws + WS_WIN) + (size_t)l * 6144 * 2048, nullptr, true, id % 128, id / 128, lane);
;             else if ((id -= 3072) < 128) conv_witem(p.in[9] + (size_t)l * 512 * 960, 512, 960, (bf16_t*)(p.ws + WS_WUQ) + (size_t)l * 1024 * 512, p.in[7] + l * 512, false, id % 32, id / 32, lane);
;             else if ((id -= 128) < 160) conv_witem(p.in[10] + (size_t)l * 512 * 1280, 512, 1280, (bf16_t*)(p.ws + WS_WUKV) + (size_t)l * 1280 * 512, p.in[8] + l * 512, false, id % 32, id / 32, lane);
;             else if ((id -= 160) < 1024) conv_witem(p.in[13] + (size_t)l * 2048 * 2048, 2048, 2048, (bf16_t*)(p.ws + WS_WO) + (size_t)l * 2048 * 2048, nullptr, false, id % 128, id / 128, lane);
;             else if ((id -= 1024) < 5632) conv_witem(p.in[16] + (size_t)l * 2048 * 11264, 2048, 11264, (bf16_t*)(p.ws + WS_WUP) + (size_t)l * 11264 * 2048, nullptr, false, id % 128, id / 128, lane, true);
;             else { id -= 5632; conv_witem(p.in[19] + (size_t)l * 5632 * 2048, 5632, 2048, (bf16_t*)(p.ws + WS_WDN) + (size_t)l * 2048 * 5632, nullptr, false, id % 352, id / 352, lane); }
.LBB0_243:
	s_or_b64 exec, exec, s[12:13]
	s_waitcnt lgkmcnt(0)
	s_barrier
	ds_read_b32 v0, v94
	s_movk_i32 s12, 47
	s_xor_b64 s[86:87], s[76:77], -1
	s_waitcnt lgkmcnt(0)
	v_cmp_lt_i32_e32 vcc, s12, v0
	v_readfirstlane_b32 s30, v0
	s_mov_b64 s[12:13], -1
	s_cbranch_vccnz .LBB0_238
	s_cmp_gt_i32 s30, 47
	s_cbranch_scc0 .LBB0_398
	v_lshl_add_u32 v0, s30, 3, v91
	s_movk_i32 s12, 0xbff
	v_cmp_lt_i32_e32 vcc, s12, v0
	s_and_saveexec_b64 s[12:13], vcc
	s_xor_b64 s[88:89], exec, s[12:13]
	s_cbranch_execz .LBB0_363
	s_movk_i32 s12, 0xc7f
	v_cmp_lt_u32_e32 vcc, s12, v0
	s_and_saveexec_b64 s[12:13], vcc
	s_xor_b64 s[16:17], exec, s[12:13]
	s_cbranch_execz .LBB0_326
	s_movk_i32 s12, 0xd1f
	v_cmp_lt_u32_e32 vcc, s12, v0
	s_and_saveexec_b64 s[12:13], vcc
	s_xor_b64 s[18:19], exec, s[12:13]
	s_cbranch_execz .LBB0_289
	s_movk_i32 s12, 0x111f
	v_cmp_lt_u32_e32 vcc, s12, v0
	s_and_saveexec_b64 s[12:13], vcc
	s_xor_b64 s[90:91], exec, s[12:13]
	s_cbranch_execz .LBB0_286
	s_movk_i32 s12, 0x271f
	v_cmp_lt_u32_e32 vcc, s12, v0
	s_and_saveexec_b64 s[12:13], vcc
	s_xor_b64 s[92:93], exec, s[12:13]
	s_cbranch_execz .LBB0_283
	v_add_u32_e32 v2, 0xffffd8e0, v0
	s_mov_b32 s12, 0xba2e8ba3
	v_mul_hi_u32 v3, v2, s12
	v_lshrrev_b32_e32 v0, 8, v3
	v_mul_u32_u24_e32 v0, 0x160, v0
	v_sub_u32_e32 v0, v2, v0
	s_movk_i32 s12, 0xff00
	v_lshlrev_b32_e32 v0, 4, v0
	v_and_or_b32 v66, v3, s12, v83
	s_movk_i32 s12, 0xb00
	v_readlane_b32 s94, v253, 17
	v_cmp_gt_u32_e64 s[12:13], s12, v2
	v_lshlrev_b64 v[2:3], 13, v[0:1]
	v_readlane_b32 s95, v253, 18
	v_mov_b32_e32 v67, v1
	v_mov_b32_e32 v6, 0
	v_lshl_add_u64 v[2:3], s[94:95], 0, v[2:3]
	v_lshl_add_u64 v[78:79], v[66:67], 2, v[2:3]
	v_mov_b32_e32 v2, 0
	v_mov_b32_e32 v3, 0
	v_mov_b32_e32 v4, 0
	v_mov_b32_e32 v5, 0
	s_and_saveexec_b64 s[94:95], s[12:13]
	s_cbranch_execz .LBB0_252
	global_load_dwordx4 v[2:5], v[78:79], off

; #define LAS __attribute__((address_space(3)))
; DI int otid() { int t = threadIdx.x; asm volatile("" : "+v"(t)); return t; }
; DI void prep_items(const Params& p, LAS unsigned char* lds, int l, unsigned* ctr, int max_items) {
;     const int tid = otid(), lane = tid & 63, wid = tid >> 6;
;     LAS float* s_c = (LAS float*)lds;
;     LAS float* s_red = (LAS float*)(lds + 40960);
;     volatile LAS int* slot = (volatile LAS int*)(lds + LDS_CTRL + 64);
;     constexpr int N_ADA = 48, PER_L = 12832, N_CONV = PER_L / 8;
;     const int n_tab = (l == 0) ? 48 : 0;
;     float* mod = (float*)(p.ws + WS_MOD);
;     bool have_c = false;
; DI void deferred_prep(const Params& p, LAS unsigned char* lds, int max_items) { prep_items(p, lds, 1, (unsigned*)(p.ws + WS_QCTR + 256 * 5), max_items); }
.LBB0_922:
	s_cmpk_lt_u32 s26, 96
	s_cbranch_scc1 .Ldef_skip_1
	v_writelane_b32 v254, s0, 0
	v_writelane_b32 v254, s1, 1
	v_writelane_b32 v254, s2, 2
	v_writelane_b32 v254, s3, 3
	v_writelane_b32 v254, s4, 4
	v_writelane_b32 v254, s5, 5
	v_writelane_b32 v254, s6, 6
	v_writelane_b32 v254, s7, 7
	v_writelane_b32 v254, s8, 8
	v_writelane_b32 v254, s9, 9
	v_writelane_b32 v254, s10, 10
	v_writelane_b32 v254, s11, 11
	v_writelane_b32 v254, s12, 12
	v_writelane_b32 v254, s13, 13
	v_writelane_b32 v254, s14, 14
	v_writelane_b32 v254, s15, 15
	v_writelane_b32 v254, s16, 16
	v_writelane_b32 v254, s17, 17
	v_writelane_b32 v254, s18, 18
	v_writelane_b32 v254, s19, 19
	v_writelane_b32 v254, s20, 20
	v_writelane_b32 v254, s21, 21
	v_writelane_b32 v254, s22, 22
	v_writelane_b32 v254, s23, 23
	v_writelane_b32 v254, s24, 24
	v_writelane_b32 v254, s25, 25
	v_writelane_b32 v254, s26, 26
	v_writelane_b32 v254, s27, 27
	v_writelane_b32 v254, s28, 28
	v_writelane_b32 v254, s29, 29
	v_writelane_b32 v254, s30, 30
	v_writelane_b32 v254, s31, 31
	v_writelane_b32 v254, s32, 32
	v_writelane_b32 v254, s33, 33
	v_writelane_b32 v254, s34, 34
	v_writelane_b32 v254, s35, 35
	v_writelane_b32 v254, s36, 36
	v_writelane_b32 v254, s37, 37
	v_writelane_b32 v254, s38, 38
	v_writelane_b32 v254, s39, 39
	v_writelane_b32 v254, s40, 40
	v_writelane_b32 v254, s41, 41
	v_writelane_b32 v254, s42, 42
	v_writelane_b32 v254, s43, 43
	v_writelane_b32 v254, s44, 44
	v_writelane_b32 v254, s45, 45
	v_writelane_b32 v254, s46, 46
	v_writelane_b32 v254, s47, 47
	v_writelane_b32 v254, s48, 48
	v_writelane_b32 v254, s49, 49
	v_writelane_b32 v254, s50, 50
	v_writelane_b32 v254, s51, 51
	v_writelane_b32 v254, s52, 52
	v_writelane_b32 v254, s53, 53
	v_writelane_b32 v254, s54, 54
	v_writelane_b32 v254, s55, 55
	v_writelane_b32 v254, s56, 56
	v_writelane_b32 v254, s57, 57
	v_writelane_b32 v254, s58, 58
	v_writelane_b32 v254, s59, 59
	v_writelane_b32 v254, s60, 60
	v_writelane_b32 v254, s61, 61
	v_writelane_b32 v254, s62, 62
	v_writelane_b32 v254, s63, 63
	v_writelane_b32 v255, s64, 0
	v_writelane_b32 v255, s65, 1
	v_writelane_b32 v255, s66, 2
	v_writelane_b32 v255, s67, 3
	v_writelane_b32 v255, s68, 4
	v_writelane_b32 v255, s69, 5
	v_writelane_b32 v255, s70, 6
	v_writelane_b32 v255, s71, 7
	v_writelane_b32 v255, s72, 8
	v_writelane_b32 v255, s73, 9
	v_writelane_b32 v255, s74, 10
	v_writelane_b32 v255, s75, 11
	v_writelane_b32 v255, s76, 12
	v_writelane_b32 v255, s77, 13
	v_writelane_b32 v255, s78, 14
	v_writelane_b32 v255, s79, 15
	v_writelane_b32 v255, s80, 16
	v_writelane_b32 v255, s81, 17
	v_writelane_b32 v255, s82, 18
	v_writelane_b32 v255, s83, 19
	v_writelane_b32 v255, s84, 20
	v_writelane_b32 v255, s85, 21
	v_writelane_b32 v255, s86, 22
	v_writelane_b32 v255, s87, 23
	v_writelane_b32 v255, s88, 24
	v_writelane_b32 v255, s89, 25
	v_writelane_b32 v255, s90, 26
	v_writelane_b32 v255, s91, 27
	v_writelane_b32 v255, s92, 28
	v_writelane_b32 v255, s93, 29
	v_writelane_b32 v255, s94, 30
	v_writelane_b32 v255, s95, 31
	v_writelane_b32 v255, s96, 32
	v_writelane_b32 v255, s97, 33
	v_readlane_b32 s2, v253, 9
	s_nop 0
	v_writelane_b32 v255, s2, 40
	v_readlane_b32 s2, v253, 10
	s_nop 0
	v_writelane_b32 v255, s2, 41
	v_readlane_b32 s2, v253, 13
	s_nop 0
	v_writelane_b32 v255, s2, 42
	v_readlane_b32 s2, v253, 14
	s_nop 0
	v_writelane_b32 v255, s2, 43
	v_readlane_b32 s2, v253, 15
	s_nop 0
	v_writelane_b32 v255, s2, 44
	v_readlane_b32 s2, v253, 16
	s_nop 0
	v_writelane_b32 v255, s2, 45
	v_readlane_b32 s2, v253, 17
	s_nop 0
	v_writelane_b32 v255, s2, 46
	v_readlane_b32 s2, v253, 18
	s_nop 0
	v_writelane_b32 v255, s2, 47
	v_readlane_b32 s2, v255, 62
	v_readlane_b32 s3, v255, 63
	s_nop 4
	s_load_dwordx16 s[36:51], s[2:3], 0x80
	s_load_dwordx16 s[68:83], s[2:3], 0x0
	s_load_dwordx16 s[52:67], s[2:3], 0x40
	s_mov_b32 s4, -1
	s_nop 0
	v_writelane_b32 v253, s4, 9
	v_writelane_b32 v253, s4, 10
	v_writelane_b32 v253, s4, 13
	v_writelane_b32 v253, s4, 14
	s_waitcnt lgkmcnt(0)
	s_add_u32 s14, s50, 0x8000
	s_addc_u32 s15, s51, 0
	s_add_u32 s0, s50, 0x4600
	s_addc_u32 s1, s51, 0
	v_mov_b32_e32 v68, v202
	s_movk_i32 s6, 0x3000
	s_movk_i32 s94, 0x1400
	v_or_b32_sdwa v90, v68, s6 dst_sel:DWORD dst_unused:UNUSED_PAD src0_sel:BYTE_0 src1_sel:DWORD
	s_add_u32 s6, s42, 0x2c00000
	s_addc_u32 s7, s43, 0
	s_add_u32 s22, s50, 0xb5a0000
	s_addc_u32 s23, s51, 0
	s_add_u32 s28, s36, 0x5800000
	v_writelane_b32 v253, s6, 17
	s_addc_u32 s29, s37, 0
	v_and_b32_e32 v0, 63, v68
	v_writelane_b32 v253, s7, 18
	s_add_u32 s6, s50, 0x73a0000
	s_addc_u32 s7, s51, 0
	s_add_u32 s34, s62, 0x1000000
	s_addc_u32 s35, s63, 0
	s_add_u32 s36, s50, 0x3fa0000
	s_addc_u32 s37, s51, 0
	v_lshlrev_b32_e32 v83, 2, v0
	v_lshlrev_b32_e32 v2, 1, v68
	s_add_u32 s42, s56, 0x280000
	v_and_b32_e32 v1, 28, v83
	v_and_b32_e32 v2, 16, v2
	s_addc_u32 s43, s57, 0
	v_ashrrev_i32_e32 v82, 6, v68
	v_or_b32_e32 v3, v2, v1
	v_add3_u32 v2, v1, v2, 16
	v_cmp_gt_u32_e32 vcc, 16, v1
	s_add_u32 s56, s50, 0x3660000
	v_mul_lo_u32 v1, v82, s94
	v_cndmask_b32_e32 v87, v2, v3, vcc
	v_lshlrev_b32_e32 v2, 4, v0
	v_mov_b32_e32 v0, 2
	s_addc_u32 s57, s51, 0
	v_add3_u32 v88, 0, v1, v2
	v_lshlrev_b32_sdwa v0, v0, v68 dst_sel:DWORD dst_unused:UNUSED_PAD src0_sel:DWORD src1_sel:BYTE_0
	v_mov_b32_e32 v1, 0
	s_add_u32 s54, s54, 0x1e0000
	v_add_u32_e32 v89, 0, v0
	v_lshl_add_u64 v[70:71], s[14:15], 0, v[0:1]
	s_addc_u32 s55, s55, 0
	v_max_i32_e32 v0, 0x7f8, v82
	s_add_u32 s62, s50, 0x3420000
	v_sub_u32_e32 v0, v0, v82
	s_addc_u32 s63, s51, 0
	v_add_u32_e32 v0, 7, v0
	v_writelane_b32 v253, s6, 15
	s_add_u32 s80, s80, 0x2e80000
	v_lshrrev_b32_e32 v3, 3, v0
	s_mov_b32 s27, 0xc000
	v_writelane_b32 v253, s7, 16
	s_addc_u32 s81, s81, 0
	v_add_u32_e32 v3, 1, v3
	v_mad_i64_i32 v[4:5], s[6:7], v82, s27, 0
	s_add_u32 s84, s50, 0x1b20000
	v_and_b32_e32 v6, 7, v3
	v_mov_b32_e32 v3, v1
	v_or_b32_e32 v4, v4, v2
	s_movk_i32 s2, 0x2800
	s_movk_i32 s4, 0x800
	s_movk_i32 s97, 0x500
	s_addc_u32 s85, s51, 0
	v_and_b32_e32 v7, 56, v0
	v_ashrrev_i32_e32 v69, 31, v68
	v_lshl_add_u64 v[4:5], s[76:77], 0, v[4:5]
	s_mov_b64 s[6:7], 0x6000000
	v_lshl_add_u64 v[2:3], s[76:77], 0, v[2:3]
	s_add_i32 s20, 0, 0x22040
	v_and_b32_e32 v84, 0x7c, v83
	v_or_b32_e32 v85, 0xffff9c00, v83
	v_or_b32_e32 v86, 0xffffa000, v83
	v_cmp_gt_i32_e64 s[2:3], s2, v68
	v_cmp_gt_i32_e64 s[4:5], s4, v82
	s_mov_b32 s96, 0x3ffffff9
	v_add_u32_e32 v91, 0xfffffe80, v82
	v_lshl_add_u32 v92, v68, 2, 0
	v_lshl_add_u64 v[72:73], v[68:69], 2, s[70:71]
	v_lshl_add_u32 v69, v82, 2, 0
	v_lshl_add_u64 v[74:75], v[4:5], 0, s[6:7]
	v_sub_u32_e32 v93, 0, v6
	v_lshl_add_u64 v[76:77], v[2:3], 0, s[6:7]
	v_mov_b32_e32 v94, s20
	v_mov_b32_e32 v95, 0xffffea00
	v_mov_b32_e32 v96, 0x80
	s_movk_i32 s21, 0x2000
	v_cmp_gt_i32_e64 s[6:7], s97, v68
	v_cmp_ne_u32_e64 s[8:9], 56, v7
	v_cmp_lt_u32_e64 s[10:11], 55, v0
	s_mov_b64 s[76:77], 0
	s_mov_b64 s[70:71], 0x300000
	s_branch .Ldq1_239

; DI void prep_items(const Params& p, LAS unsigned char* lds, int l, unsigned* ctr, int max_items) {
;     ...
;     for (int done = 0; done < max_items; ++done) {
;         const int it = next_item(ctr, slot);
;         if (it >= N_ADA + n_tab + N_CONV) break;
;     ...
;             int id = (it - N_ADA - n_tab) * 8 + wid;
;             if (id < 3072) conv_witem(p.in[6] + (size_t)l * 2048 * INW, 2048, INW, (bf16_t*)(p.ws + WS_WIN) + (size_t)l * 6144 * 2048, nullptr, true, id % 128, id / 128, lane);
;             else if ((id -= 3072) < 128) conv_witem(p.in[9] + (size_t)l * 512 * 960, 512, 960, (bf16_t*)(p.ws + WS_WUQ) + (size_t)l * 1024 * 512, p.in[7] + l * 512, false, id % 32, id / 32, lane);
;             else if ((id -= 128) < 160) conv_witem(p.in[10] + (size_t)l * 512 * 1280, 512, 1280, (bf16_t*)(p.ws + WS_WUKV) + (size_t)l * 1280 * 512, p.in[8] + l * 512, false, id % 32, id / 32, lane);
;             else if ((id -= 160) < 1024) conv_witem(p.in[13] + (size_t)l * 2048 * 2048, 2048, 2048, (bf16_t*)(p.ws + WS_WO) + (size_t)l * 2048 * 2048, nullptr, false, id % 128, id / 128, lane);
;             else if ((id -= 1024) < 5632) conv_witem(p.in[16] + (size_t)l * 2048 * 11264, 2048, 11264, (bf16_t*)(p.ws + WS_WUP) + (size_t)l * 11264 * 2048, nullptr, false, id % 128, id / 128, lane, true);
;             else { id -= 5632; conv_witem(p.in[19] + (size_t)l * 5632 * 2048, 5632, 2048, (bf16_t*)(p.ws + WS_WDN) + (size_t)l * 2048 * 5632, nullptr, false, id % 352, id / 352, lane); }
.Ldq1_243:
	s_or_b64 exec, exec, s[12:13]
	s_waitcnt lgkmcnt(0)
	s_barrier
	ds_read_b32 v0, v94
	s_movk_i32 s12, 0x673
	s_xor_b64 s[86:87], s[76:77], -1
	s_waitcnt lgkmcnt(0)
	v_add_u32_e32 v0, 48, v0
	v_cmp_lt_i32_e32 vcc, s12, v0
	v_readfirstlane_b32 s30, v0
	s_mov_b64 s[12:13], -1
	s_cbranch_vccnz .Ldq1_238
	s_cmp_gt_i32 s30, 47
	s_cbranch_scc0 .Ldq1_398
	v_lshl_add_u32 v0, s30, 3, v91
	s_movk_i32 s12, 0xbff
	v_cmp_lt_i32_e32 vcc, s12, v0
	s_and_saveexec_b64 s[12:13], vcc
	s_xor_b64 s[88:89], exec, s[12:13]
	s_cbranch_execz .Ldq1_363
	s_movk_i32 s12, 0xc7f
	v_cmp_lt_u32_e32 vcc, s12, v0
	s_and_saveexec_b64 s[12:13], vcc
	s_xor_b64 s[16:17], exec, s[12:13]
	s_cbranch_execz .Ldq1_326
	s_movk_i32 s12, 0xd1f
	v_cmp_lt_u32_e32 vcc, s12, v0
	s_and_saveexec_b64 s[12:13], vcc
	s_xor_b64 s[18:19], exec, s[12:13]
	s_cbranch_execz .Ldq1_289
	s_movk_i32 s12, 0x111f
	v_cmp_lt_u32_e32 vcc, s12, v0
	s_and_saveexec_b64 s[12:13], vcc
	s_xor_b64 s[90:91], exec, s[12:13]
	s_cbranch_execz .Ldq1_286
	s_movk_i32 s12, 0x271f
	v_cmp_lt_u32_e32 vcc, s12, v0
	s_and_saveexec_b64 s[12:13], vcc
	s_xor_b64 s[92:93], exec, s[12:13]
	s_cbranch_execz .Ldq1_283
	v_add_u32_e32 v2, 0xffffd8e0, v0
	s_mov_b32 s12, 0xba2e8ba3
	v_mul_hi_u32 v3, v2, s12
	v_lshrrev_b32_e32 v0, 8, v3
	v_mul_u32_u24_e32 v0, 0x160, v0
	v_sub_u32_e32 v0, v2, v0
	s_movk_i32 s12, 0xff00
	v_lshlrev_b32_e32 v0, 4, v0
	v_and_or_b32 v66, v3, s12, v83
	s_movk_i32 s12, 0xb00
	v_readlane_b32 s94, v253, 17
	v_cmp_gt_u32_e64 s[12:13], s12, v2
	v_lshlrev_b64 v[2:3], 13, v[0:1]
	v_readlane_b32 s95, v253, 18
	v_mov_b32_e32 v67, v1
	v_mov_b32_e32 v6, 0
	v_lshl_add_u64 v[2:3], s[94:95], 0, v[2:3]
	v_lshl_add_u64 v[78:79], v[66:67], 2, v[2:3]
	v_mov_b32_e32 v2, 0
	v_mov_b32_e32 v3, 0
	v_mov_b32_e32 v4, 0
	v_mov_b32_e32 v5, 0
	s_and_saveexec_b64 s[94:95], s[12:13]
	s_cbranch_execz .Ldq1_252
	global_load_dwordx4 v[2:5], v[78:79], off

; #define LAS __attribute__((address_space(3)))
; DI void prep_items(const Params& p, LAS unsigned char* lds, int l, unsigned* ctr, int max_items) {
;     ...
;     }
;     __syncthreads();
; DI void deferred_prep(const Params& p, LAS unsigned char* lds, int max_items) { prep_items(p, lds, 1, (unsigned*)(p.ws + WS_QCTR + 256 * 5), max_items); }
.Ldq1_417:
	s_barrier
	v_readlane_b32 s2, v255, 40
	s_nop 0
	v_writelane_b32 v253, s2, 9
	v_readlane_b32 s2, v255, 41
	s_nop 0
	v_writelane_b32 v253, s2, 10
	v_readlane_b32 s2, v255, 42
	s_nop 0
	v_writelane_b32 v253, s2, 13
	v_readlane_b32 s2, v255, 43
	s_nop 0
	v_writelane_b32 v253, s2, 14
	v_readlane_b32 s2, v255, 44
	s_nop 0
	v_writelane_b32 v253, s2, 15
	v_readlane_b32 s2, v255, 45
	s_nop 0
	v_writelane_b32 v253, s2, 16
	v_readlane_b32 s2, v255, 46
	s_nop 0
	v_writelane_b32 v253, s2, 17
	v_readlane_b32 s2, v255, 47
	s_nop 0
	v_writelane_b32 v253, s2, 18
	v_readlane_b32 s0, v254, 0
	v_readlane_b32 s1, v254, 1
	v_readlane_b32 s2, v254, 2
	v_readlane_b32 s3, v254, 3
	v_readlane_b32 s4, v254, 4
	v_readlane_b32 s5, v254, 5
	v_readlane_b32 s6, v254, 6
	v_readlane_b32 s7, v254, 7
	v_readlane_b32 s8, v254, 8
	v_readlane_b32 s9, v254, 9
	v_readlane_b32 s10, v254, 10
	v_readlane_b32 s11, v254, 11
	v_readlane_b32 s12, v254, 12
	v_readlane_b32 s13, v254, 13
	v_readlane_b32 s14, v254, 14
	v_readlane_b32 s15, v254, 15
	v_readlane_b32 s16, v254, 16
	v_readlane_b32 s17, v254, 17
	v_readlane_b32 s18, v254, 18
	v_readlane_b32 s19, v254, 19
	v_readlane_b32 s20, v254, 20
	v_readlane_b32 s21, v254, 21
	v_readlane_b32 s22, v254, 22
	v_readlane_b32 s23, v254, 23
	v_readlane_b32 s24, v254, 24
	v_readlane_b32 s25, v254, 25
	v_readlane_b32 s26, v254, 26
	v_readlane_b32 s27, v254, 27
	v_readlane_b32 s28, v254, 28
	v_readlane_b32 s29, v254, 29
	v_readlane_b32 s30, v254, 30
	v_readlane_b32 s31, v254, 31
	v_readlane_b32 s32, v254, 32
	v_readlane_b32 s33, v254, 33
	v_readlane_b32 s34, v254, 34
	v_readlane_b32 s35, v254, 35
	v_readlane_b32 s36, v254, 36
	v_readlane_b32 s37, v254, 37
	v_readlane_b32 s38, v254, 38
	v_readlane_b32 s39, v254, 39
	v_readlane_b32 s40, v254, 40
	v_readlane_b32 s41, v254, 41
	v_readlane_b32 s42, v254, 42
	v_readlane_b32 s43, v254, 43
	v_readlane_b32 s44, v254, 44
	v_readlane_b32 s45, v254, 45
	v_readlane_b32 s46, v254, 46
	v_readlane_b32 s47, v254, 47
	v_readlane_b32 s48, v254, 48
	v_readlane_b32 s49, v254, 49
	v_readlane_b32 s50, v254, 50
	v_readlane_b32 s51, v254, 51
	v_readlane_b32 s52, v254, 52
	v_readlane_b32 s53, v254, 53
	v_readlane_b32 s54, v254, 54
	v_readlane_b32 s55, v254, 55
	v_readlane_b32 s56, v254, 56
	v_readlane_b32 s57, v254, 57
	v_readlane_b32 s58, v254, 58
	v_readlane_b32 s59, v254, 59
	v_readlane_b32 s60, v254, 60
	v_readlane_b32 s61, v254, 61
	v_readlane_b32 s62, v254, 62
	v_readlane_b32 s63, v254, 63
	v_readlane_b32 s64, v255, 0
	v_readlane_b32 s65, v255, 1
	v_readlane_b32 s66, v255, 2
	v_readlane_b32 s67, v255, 3
	v_readlane_b32 s68, v255, 4
	v_readlane_b32 s69, v255, 5
	v_readlane_b32 s70, v255, 6
	v_readlane_b32 s71, v255, 7
	v_readlane_b32 s72, v255, 8
	v_readlane_b32 s73, v255, 9
	v_readlane_b32 s74, v255, 10
	v_readlane_b32 s75, v255, 11
	v_readlane_b32 s76, v255, 12
	v_readlane_b32 s77, v255, 13
	v_readlane_b32 s78, v255, 14
	v_readlane_b32 s79, v255, 15
	v_readlane_b32 s80, v255, 16
	v_readlane_b32 s81, v255, 17
	v_readlane_b32 s82, v255, 18
	v_readlane_b32 s83, v255, 19
	v_readlane_b32 s84, v255, 20
	v_readlane_b32 s85, v255, 21
	v_readlane_b32 s86, v255, 22
	v_readlane_b32 s87, v255, 23
	v_readlane_b32 s88, v255, 24
	v_readlane_b32 s89, v255, 25
	v_readlane_b32 s90, v255, 26
	v_readlane_b32 s91, v255, 27
	v_readlane_b32 s92, v255, 28
	v_readlane_b32 s93, v255, 29
	v_readlane_b32 s94, v255, 30
	v_readlane_b32 s95, v255, 31
	v_readlane_b32 s96, v255, 32
	v_readlane_b32 s97, v255, 33
	s_nop 4

; #define LAS __attribute__((address_space(3)))
; DI int otid() { int t = threadIdx.x; asm volatile("" : "+v"(t)); return t; }
; DI void prep_items(const Params& p, LAS unsigned char* lds, int l, unsigned* ctr, int max_items) {
;     const int tid = otid(), lane = tid & 63, wid = tid >> 6;
;     LAS float* s_c = (LAS float*)lds;
;     LAS float* s_red = (LAS float*)(lds + 40960);
;     volatile LAS int* slot = (volatile LAS int*)(lds + LDS_CTRL + 64);
;     constexpr int N_ADA = 48, PER_L = 12832, N_CONV = PER_L / 8;
;     const int n_tab = (l == 0) ? 48 : 0;
;     float* mod = (float*)(p.ws + WS_MOD);
;     bool have_c = false;
; DI void deferred_prep(const Params& p, LAS unsigned char* lds, int max_items) { prep_items(p, lds, 1, (unsigned*)(p.ws + WS_QCTR + 256 * 5), max_items); }
.LBB0_1541:
	s_cmpk_lt_u32 s26, 48
	s_cbranch_scc1 .Ldef_skip_2
	v_writelane_b32 v254, s0, 0
	v_writelane_b32 v254, s1, 1
	v_writelane_b32 v254, s2, 2
	v_writelane_b32 v254, s3, 3
	v_writelane_b32 v254, s4, 4
	v_writelane_b32 v254, s5, 5
	v_writelane_b32 v254, s6, 6
	v_writelane_b32 v254, s7, 7
	v_writelane_b32 v254, s8, 8
	v_writelane_b32 v254, s9, 9
	v_writelane_b32 v254, s10, 10
	v_writelane_b32 v254, s11, 11
	v_writelane_b32 v254, s12, 12
	v_writelane_b32 v254, s13, 13
	v_writelane_b32 v254, s14, 14
	v_writelane_b32 v254, s15, 15
	v_writelane_b32 v254, s16, 16
	v_writelane_b32 v254, s17, 17
	v_writelane_b32 v254, s18, 18
	v_writelane_b32 v254, s19, 19
	v_writelane_b32 v254, s20, 20
	v_writelane_b32 v254, s21, 21
	v_writelane_b32 v254, s22, 22
	v_writelane_b32 v254, s23, 23
	v_writelane_b32 v254, s24, 24
	v_writelane_b32 v254, s25, 25
	v_writelane_b32 v254, s26, 26
	v_writelane_b32 v254, s27, 27
	v_writelane_b32 v254, s28, 28
	v_writelane_b32 v254, s29, 29
	v_writelane_b32 v254, s30, 30
	v_writelane_b32 v254, s31, 31
	v_writelane_b32 v254, s32, 32
	v_writelane_b32 v254, s33, 33
	v_writelane_b32 v254, s34, 34
	v_writelane_b32 v254, s35, 35
	v_writelane_b32 v254, s36, 36
	v_writelane_b32 v254, s37, 37
	v_writelane_b32 v254, s38, 38
	v_writelane_b32 v254, s39, 39
	v_writelane_b32 v254, s40, 40
	v_writelane_b32 v254, s41, 41
	v_writelane_b32 v254, s42, 42
	v_writelane_b32 v254, s43, 43
	v_writelane_b32 v254, s44, 44
	v_writelane_b32 v254, s45, 45
	v_writelane_b32 v254, s46, 46
	v_writelane_b32 v254, s47, 47
	v_writelane_b32 v254, s48, 48
	v_writelane_b32 v254, s49, 49
	v_writelane_b32 v254, s50, 50
	v_writelane_b32 v254, s51, 51
	v_writelane_b32 v254, s52, 52
	v_writelane_b32 v254, s53, 53
	v_writelane_b32 v254, s54, 54
	v_writelane_b32 v254, s55, 55
	v_writelane_b32 v254, s56, 56
	v_writelane_b32 v254, s57, 57
	v_writelane_b32 v254, s58, 58
	v_writelane_b32 v254, s59, 59
	v_writelane_b32 v254, s60, 60
	v_writelane_b32 v254, s61, 61
	v_writelane_b32 v254, s62, 62
	v_writelane_b32 v254, s63, 63
	v_writelane_b32 v255, s64, 0
	v_writelane_b32 v255, s65, 1
	v_writelane_b32 v255, s66, 2
	v_writelane_b32 v255, s67, 3
	v_writelane_b32 v255, s68, 4
	v_writelane_b32 v255, s69, 5
	v_writelane_b32 v255, s70, 6
	v_writelane_b32 v255, s71, 7
	v_writelane_b32 v255, s72, 8
	v_writelane_b32 v255, s73, 9
	v_writelane_b32 v255, s74, 10
	v_writelane_b32 v255, s75, 11
	v_writelane_b32 v255, s76, 12
	v_writelane_b32 v255, s77, 13
	v_writelane_b32 v255, s78, 14
	v_writelane_b32 v255, s79, 15
	v_writelane_b32 v255, s80, 16
	v_writelane_b32 v255, s81, 17
	v_writelane_b32 v255, s82, 18
	v_writelane_b32 v255, s83, 19
	v_writelane_b32 v255, s84, 20
	v_writelane_b32 v255, s85, 21
	v_writelane_b32 v255, s86, 22
	v_writelane_b32 v255, s87, 23
	v_writelane_b32 v255, s88, 24
	v_writelane_b32 v255, s89, 25
	v_writelane_b32 v255, s90, 26
	v_writelane_b32 v255, s91, 27
	v_writelane_b32 v255, s92, 28
	v_writelane_b32 v255, s93, 29
	v_writelane_b32 v255, s94, 30
	v_writelane_b32 v255, s95, 31
	v_writelane_b32 v255, s96, 32
	v_writelane_b32 v255, s97, 33
	v_readlane_b32 s2, v253, 9
	s_nop 0
	v_writelane_b32 v255, s2, 40
	v_readlane_b32 s2, v253, 10
	s_nop 0
	v_writelane_b32 v255, s2, 41
	v_readlane_b32 s2, v253, 13
	s_nop 0
	v_writelane_b32 v255, s2, 42
	v_readlane_b32 s2, v253, 14
	s_nop 0
	v_writelane_b32 v255, s2, 43
	v_readlane_b32 s2, v253, 15
	s_nop 0
	v_writelane_b32 v255, s2, 44
	v_readlane_b32 s2, v253, 16
	s_nop 0
	v_writelane_b32 v255, s2, 45
	v_readlane_b32 s2, v253, 17
	s_nop 0
	v_writelane_b32 v255, s2, 46
	v_readlane_b32 s2, v253, 18
	s_nop 0
	v_writelane_b32 v255, s2, 47
	v_readlane_b32 s2, v255, 62
	v_readlane_b32 s3, v255, 63
	s_nop 4
	s_load_dwordx16 s[36:51], s[2:3], 0x80
	s_load_dwordx16 s[68:83], s[2:3], 0x0
	s_load_dwordx16 s[52:67], s[2:3], 0x40
	s_mov_b32 s4, -1
	s_nop 0
	v_writelane_b32 v253, s4, 9
	v_writelane_b32 v253, s4, 10
	v_writelane_b32 v253, s4, 13
	v_writelane_b32 v253, s4, 14
	s_waitcnt lgkmcnt(0)
	s_add_u32 s14, s50, 0x8000
	s_addc_u32 s15, s51, 0
	s_add_u32 s0, s50, 0x4600
	s_addc_u32 s1, s51, 0
	v_mov_b32_e32 v68, v202
	s_movk_i32 s6, 0x3000
	s_movk_i32 s94, 0x1400
	v_or_b32_sdwa v90, v68, s6 dst_sel:DWORD dst_unused:UNUSED_PAD src0_sel:BYTE_0 src1_sel:DWORD
	s_add_u32 s6, s42, 0x2c00000
	s_addc_u32 s7, s43, 0
	s_add_u32 s22, s50, 0xb5a0000
	s_addc_u32 s23, s51, 0
	s_add_u32 s28, s36, 0x5800000
	v_writelane_b32 v253, s6, 17
	s_addc_u32 s29, s37, 0
	v_and_b32_e32 v0, 63, v68
	v_writelane_b32 v253, s7, 18
	s_add_u32 s6, s50, 0x73a0000
	s_addc_u32 s7, s51, 0
	s_add_u32 s34, s62, 0x1000000
	s_addc_u32 s35, s63, 0
	s_add_u32 s36, s50, 0x3fa0000
	s_addc_u32 s37, s51, 0
	v_lshlrev_b32_e32 v83, 2, v0
	v_lshlrev_b32_e32 v2, 1, v68
	s_add_u32 s42, s56, 0x280000
	v_and_b32_e32 v1, 28, v83
	v_and_b32_e32 v2, 16, v2
	s_addc_u32 s43, s57, 0
	v_ashrrev_i32_e32 v82, 6, v68
	v_or_b32_e32 v3, v2, v1
	v_add3_u32 v2, v1, v2, 16
	v_cmp_gt_u32_e32 vcc, 16, v1
	s_add_u32 s56, s50, 0x3660000
	v_mul_lo_u32 v1, v82, s94
	v_cndmask_b32_e32 v87, v2, v3, vcc
	v_lshlrev_b32_e32 v2, 4, v0
	v_mov_b32_e32 v0, 2
	s_addc_u32 s57, s51, 0
	v_add3_u32 v88, 0, v1, v2
	v_lshlrev_b32_sdwa v0, v0, v68 dst_sel:DWORD dst_unused:UNUSED_PAD src0_sel:DWORD src1_sel:BYTE_0
	v_mov_b32_e32 v1, 0
	s_add_u32 s54, s54, 0x1e0000
	v_add_u32_e32 v89, 0, v0
	v_lshl_add_u64 v[70:71], s[14:15], 0, v[0:1]
	s_addc_u32 s55, s55, 0
	v_max_i32_e32 v0, 0x7f8, v82
	s_add_u32 s62, s50, 0x3420000
	v_sub_u32_e32 v0, v0, v82
	s_addc_u32 s63, s51, 0
	v_add_u32_e32 v0, 7, v0
	v_writelane_b32 v253, s6, 15
	s_add_u32 s80, s80, 0x2e80000
	v_lshrrev_b32_e32 v3, 3, v0
	s_mov_b32 s27, 0xc000
	v_writelane_b32 v253, s7, 16
	s_addc_u32 s81, s81, 0
	v_add_u32_e32 v3, 1, v3
	v_mad_i64_i32 v[4:5], s[6:7], v82, s27, 0
	s_add_u32 s84, s50, 0x1b20000
	v_and_b32_e32 v6, 7, v3
	v_mov_b32_e32 v3, v1
	v_or_b32_e32 v4, v4, v2
	s_movk_i32 s2, 0x2800
	s_movk_i32 s4, 0x800
	s_movk_i32 s97, 0x500
	s_addc_u32 s85, s51, 0
	v_and_b32_e32 v7, 56, v0
	v_ashrrev_i32_e32 v69, 31, v68
	v_lshl_add_u64 v[4:5], s[76:77], 0, v[4:5]
	s_mov_b64 s[6:7], 0x6000000
	v_lshl_add_u64 v[2:3], s[76:77], 0, v[2:3]
	s_add_i32 s20, 0, 0x22040
	v_and_b32_e32 v84, 0x7c, v83
	v_or_b32_e32 v85, 0xffff9c00, v83
	v_or_b32_e32 v86, 0xffffa000, v83
	v_cmp_gt_i32_e64 s[2:3], s2, v68
	v_cmp_gt_i32_e64 s[4:5], s4, v82
	s_mov_b32 s96, 0x3ffffffa
	v_add_u32_e32 v91, 0xfffffe80, v82
	v_lshl_add_u32 v92, v68, 2, 0
	v_lshl_add_u64 v[72:73], v[68:69], 2, s[70:71]
	v_lshl_add_u32 v69, v82, 2, 0
	v_lshl_add_u64 v[74:75], v[4:5], 0, s[6:7]
	v_sub_u32_e32 v93, 0, v6
	v_lshl_add_u64 v[76:77], v[2:3], 0, s[6:7]
	v_mov_b32_e32 v94, s20
	v_mov_b32_e32 v95, 0xffffea00
	v_mov_b32_e32 v96, 0x80
	s_movk_i32 s21, 0x2000
	v_cmp_gt_i32_e64 s[6:7], s97, v68
	v_cmp_ne_u32_e64 s[8:9], 56, v7
	v_cmp_lt_u32_e64 s[10:11], 55, v0
	s_mov_b64 s[76:77], 0
	s_mov_b64 s[70:71], 0x300000
	s_branch .Ldq2_239

; #define LAS __attribute__((address_space(3)))
; DI int otid() { int t = threadIdx.x; asm volatile("" : "+v"(t)); return t; }
; DI void prep_items(const Params& p, LAS unsigned char* lds, int l, unsigned* ctr, int max_items) {
;     const int tid = otid(), lane = tid & 63, wid = tid >> 6;
;     LAS float* s_c = (LAS float*)lds;
;     LAS float* s_red = (LAS float*)(lds + 40960);
;     volatile LAS int* slot = (volatile LAS int*)(lds + LDS_CTRL + 64);
;     constexpr int N_ADA = 48, PER_L = 12832, N_CONV = PER_L / 8;
;     const int n_tab = (l == 0) ? 48 : 0;
;     float* mod = (float*)(p.ws + WS_MOD);
;     bool have_c = false;
; DI void deferred_prep(const Params& p, LAS unsigned char* lds, int max_items) { prep_items(p, lds, 1, (unsigned*)(p.ws + WS_QCTR + 256 * 5), max_items); }
.LBB0_1788:
	s_cmpk_lt_u32 s26, 128
	s_cbranch_scc1 .Ldef_skip_3
	v_writelane_b32 v254, s0, 0
	v_writelane_b32 v254, s1, 1
	v_writelane_b32 v254, s2, 2
	v_writelane_b32 v254, s3, 3
	v_writelane_b32 v254, s4, 4
	v_writelane_b32 v254, s5, 5
	v_writelane_b32 v254, s6, 6
	v_writelane_b32 v254, s7, 7
	v_writelane_b32 v254, s8, 8
	v_writelane_b32 v254, s9, 9
	v_writelane_b32 v254, s10, 10
	v_writelane_b32 v254, s11, 11
	v_writelane_b32 v254, s12, 12
	v_writelane_b32 v254, s13, 13
	v_writelane_b32 v254, s14, 14
	v_writelane_b32 v254, s15, 15
	v_writelane_b32 v254, s16, 16
	v_writelane_b32 v254, s17, 17
	v_writelane_b32 v254, s18, 18
	v_writelane_b32 v254, s19, 19
	v_writelane_b32 v254, s20, 20
	v_writelane_b32 v254, s21, 21
	v_writelane_b32 v254, s22, 22
	v_writelane_b32 v254, s23, 23
	v_writelane_b32 v254, s24, 24
	v_writelane_b32 v254, s25, 25
	v_writelane_b32 v254, s26, 26
	v_writelane_b32 v254, s27, 27
	v_writelane_b32 v254, s28, 28
	v_writelane_b32 v254, s29, 29
	v_writelane_b32 v254, s30, 30
	v_writelane_b32 v254, s31, 31
	v_writelane_b32 v254, s32, 32
	v_writelane_b32 v254, s33, 33
	v_writelane_b32 v254, s34, 34
	v_writelane_b32 v254, s35, 35
	v_writelane_b32 v254, s36, 36
	v_writelane_b32 v254, s37, 37
	v_writelane_b32 v254, s38, 38
	v_writelane_b32 v254, s39, 39
	v_writelane_b32 v254, s40, 40
	v_writelane_b32 v254, s41, 41
	v_writelane_b32 v254, s42, 42
	v_writelane_b32 v254, s43, 43
	v_writelane_b32 v254, s44, 44
	v_writelane_b32 v254, s45, 45
	v_writelane_b32 v254, s46, 46
	v_writelane_b32 v254, s47, 47
	v_writelane_b32 v254, s48, 48
	v_writelane_b32 v254, s49, 49
	v_writelane_b32 v254, s50, 50
	v_writelane_b32 v254, s51, 51
	v_writelane_b32 v254, s52, 52
	v_writelane_b32 v254, s53, 53
	v_writelane_b32 v254, s54, 54
	v_writelane_b32 v254, s55, 55
	v_writelane_b32 v254, s56, 56
	v_writelane_b32 v254, s57, 57
	v_writelane_b32 v254, s58, 58
	v_writelane_b32 v254, s59, 59
	v_writelane_b32 v254, s60, 60
	v_writelane_b32 v254, s61, 61
	v_writelane_b32 v254, s62, 62
	v_writelane_b32 v254, s63, 63
	v_writelane_b32 v255, s64, 0
	v_writelane_b32 v255, s65, 1
	v_writelane_b32 v255, s66, 2
	v_writelane_b32 v255, s67, 3
	v_writelane_b32 v255, s68, 4
	v_writelane_b32 v255, s69, 5
	v_writelane_b32 v255, s70, 6
	v_writelane_b32 v255, s71, 7
	v_writelane_b32 v255, s72, 8
	v_writelane_b32 v255, s73, 9
	v_writelane_b32 v255, s74, 10
	v_writelane_b32 v255, s75, 11
	v_writelane_b32 v255, s76, 12
	v_writelane_b32 v255, s77, 13
	v_writelane_b32 v255, s78, 14
	v_writelane_b32 v255, s79, 15
	v_writelane_b32 v255, s80, 16
	v_writelane_b32 v255, s81, 17
	v_writelane_b32 v255, s82, 18
	v_writelane_b32 v255, s83, 19
	v_writelane_b32 v255, s84, 20
	v_writelane_b32 v255, s85, 21
	v_writelane_b32 v255, s86, 22
	v_writelane_b32 v255, s87, 23
	v_writelane_b32 v255, s88, 24
	v_writelane_b32 v255, s89, 25
	v_writelane_b32 v255, s90, 26
	v_writelane_b32 v255, s91, 27
	v_writelane_b32 v255, s92, 28
	v_writelane_b32 v255, s93, 29
	v_writelane_b32 v255, s94, 30
	v_writelane_b32 v255, s95, 31
	v_writelane_b32 v255, s96, 32
	v_writelane_b32 v255, s97, 33
	v_readlane_b32 s2, v253, 9
	s_nop 0
	v_writelane_b32 v255, s2, 40
	v_readlane_b32 s2, v253, 10
	s_nop 0
	v_writelane_b32 v255, s2, 41
	v_readlane_b32 s2, v253, 13
	s_nop 0
	v_writelane_b32 v255, s2, 42
	v_readlane_b32 s2, v253, 14
	s_nop 0
	v_writelane_b32 v255, s2, 43
	v_readlane_b32 s2, v253, 15
	s_nop 0
	v_writelane_b32 v255, s2, 44
	v_readlane_b32 s2, v253, 16
	s_nop 0
	v_writelane_b32 v255, s2, 45
	v_readlane_b32 s2, v253, 17
	s_nop 0
	v_writelane_b32 v255, s2, 46
	v_readlane_b32 s2, v253, 18
	s_nop 0
	v_writelane_b32 v255, s2, 47
	v_readlane_b32 s2, v255, 62
	v_readlane_b32 s3, v255, 63
	s_nop 4
	s_load_dwordx16 s[36:51], s[2:3], 0x80
	s_load_dwordx16 s[68:83], s[2:3], 0x0
	s_load_dwordx16 s[52:67], s[2:3], 0x40
	s_mov_b32 s4, -1
	s_nop 0
	v_writelane_b32 v253, s4, 9
	v_writelane_b32 v253, s4, 10
	v_writelane_b32 v253, s4, 13
	v_writelane_b32 v253, s4, 14
	s_waitcnt lgkmcnt(0)
	s_add_u32 s14, s50, 0x8000
	s_addc_u32 s15, s51, 0
	s_add_u32 s0, s50, 0x4600
	s_addc_u32 s1, s51, 0
	v_mov_b32_e32 v68, v202
	s_movk_i32 s6, 0x3000
	s_movk_i32 s94, 0x1400
	v_or_b32_sdwa v90, v68, s6 dst_sel:DWORD dst_unused:UNUSED_PAD src0_sel:BYTE_0 src1_sel:DWORD
	s_add_u32 s6, s42, 0x2c00000
	s_addc_u32 s7, s43, 0
	s_add_u32 s22, s50, 0xb5a0000
	s_addc_u32 s23, s51, 0
	s_add_u32 s28, s36, 0x5800000
	v_writelane_b32 v253, s6, 17
	s_addc_u32 s29, s37, 0
	v_and_b32_e32 v0, 63, v68
	v_writelane_b32 v253, s7, 18
	s_add_u32 s6, s50, 0x73a0000
	s_addc_u32 s7, s51, 0
	s_add_u32 s34, s62, 0x1000000
	s_addc_u32 s35, s63, 0
	s_add_u32 s36, s50, 0x3fa0000
	s_addc_u32 s37, s51, 0
	v_lshlrev_b32_e32 v83, 2, v0
	v_lshlrev_b32_e32 v2, 1, v68
	s_add_u32 s42, s56, 0x280000
	v_and_b32_e32 v1, 28, v83
	v_and_b32_e32 v2, 16, v2
	s_addc_u32 s43, s57, 0
	v_ashrrev_i32_e32 v82, 6, v68
	v_or_b32_e32 v3, v2, v1
	v_add3_u32 v2, v1, v2, 16
	v_cmp_gt_u32_e32 vcc, 16, v1
	s_add_u32 s56, s50, 0x3660000
	v_mul_lo_u32 v1, v82, s94
	v_cndmask_b32_e32 v87, v2, v3, vcc
	v_lshlrev_b32_e32 v2, 4, v0
	v_mov_b32_e32 v0, 2
	s_addc_u32 s57, s51, 0
	v_add3_u32 v88, 0, v1, v2
	v_lshlrev_b32_sdwa v0, v0, v68 dst_sel:DWORD dst_unused:UNUSED_PAD src0_sel:DWORD src1_sel:BYTE_0
	v_mov_b32_e32 v1, 0
	s_add_u32 s54, s54, 0x1e0000
	v_add_u32_e32 v89, 0, v0
	v_lshl_add_u64 v[70:71], s[14:15], 0, v[0:1]
	s_addc_u32 s55, s55, 0
	v_max_i32_e32 v0, 0x7f8, v82
	s_add_u32 s62, s50, 0x3420000
	v_sub_u32_e32 v0, v0, v82
	s_addc_u32 s63, s51, 0
	v_add_u32_e32 v0, 7, v0
	v_writelane_b32 v253, s6, 15
	s_add_u32 s80, s80, 0x2e80000
	v_lshrrev_b32_e32 v3, 3, v0
	s_mov_b32 s27, 0xc000
	v_writelane_b32 v253, s7, 16
	s_addc_u32 s81, s81, 0
	v_add_u32_e32 v3, 1, v3
	v_mad_i64_i32 v[4:5], s[6:7], v82, s27, 0
	s_add_u32 s84, s50, 0x1b20000
	v_and_b32_e32 v6, 7, v3
	v_mov_b32_e32 v3, v1
	v_or_b32_e32 v4, v4, v2
	s_movk_i32 s2, 0x2800
	s_movk_i32 s4, 0x800
	s_movk_i32 s97, 0x500
	s_addc_u32 s85, s51, 0
	v_and_b32_e32 v7, 56, v0
	v_ashrrev_i32_e32 v69, 31, v68
	v_lshl_add_u64 v[4:5], s[76:77], 0, v[4:5]
	s_mov_b64 s[6:7], 0x6000000
	v_lshl_add_u64 v[2:3], s[76:77], 0, v[2:3]
	s_add_i32 s20, 0, 0x22040
	v_and_b32_e32 v84, 0x7c, v83
	v_or_b32_e32 v85, 0xffff9c00, v83
	v_or_b32_e32 v86, 0xffffa000, v83
	v_cmp_gt_i32_e64 s[2:3], s2, v68
	v_cmp_gt_i32_e64 s[4:5], s4, v82
	s_mov_b32 s96, 0x40000000
	v_add_u32_e32 v91, 0xfffffe80, v82
	v_lshl_add_u32 v92, v68, 2, 0
	v_lshl_add_u64 v[72:73], v[68:69], 2, s[70:71]
	v_lshl_add_u32 v69, v82, 2, 0
	v_lshl_add_u64 v[74:75], v[4:5], 0, s[6:7]
	v_sub_u32_e32 v93, 0, v6
	v_lshl_add_u64 v[76:77], v[2:3], 0, s[6:7]
	v_mov_b32_e32 v94, s20
	v_mov_b32_e32 v95, 0xffffea00
	v_mov_b32_e32 v96, 0x80
	s_movk_i32 s21, 0x2000
	v_cmp_gt_i32_e64 s[6:7], s97, v68
	v_cmp_ne_u32_e64 s[8:9], 56, v7
	v_cmp_lt_u32_e64 s[10:11], 55, v0
	s_mov_b64 s[76:77], 0
	s_mov_b64 s[70:71], 0x300000
	s_branch .Ldq3_239

; __global__ void __launch_bounds__(512, 2) fwd_kernel(Params p) {
;     extern __shared__ __attribute__((aligned(16))) unsigned char smem[];
	.amdhsa_kernel _Z10fwd_kernel6Params
		.amdhsa_group_segment_fixed_size 0
		.amdhsa_private_segment_fixed_size 0
		.amdhsa_kernarg_size 456
		.amdhsa_user_sgpr_count 2
		.amdhsa_user_sgpr_dispatch_ptr 0
		.amdhsa_user_sgpr_queue_ptr 0
		.amdhsa_user_sgpr_kernarg_segment_ptr 1
		.amdhsa_user_sgpr_dispatch_id 0
		.amdhsa_user_sgpr_kernarg_preload_length 0
		.amdhsa_user_sgpr_kernarg_preload_offset 0
		.amdhsa_user_sgpr_private_segment_size 0
		.amdhsa_uses_dynamic_stack 0
		.amdhsa_enable_private_segment 0
		.amdhsa_system_sgpr_workgroup_id_x 1
		.amdhsa_system_sgpr_workgroup_id_y 0
		.amdhsa_system_sgpr_workgroup_id_z 0
		.amdhsa_system_sgpr_workgroup_info 0
		.amdhsa_system_vgpr_workitem_id 2
		.amdhsa_next_free_vgpr 256
		.amdhsa_next_free_sgpr 98
		.amdhsa_accum_offset 256
		.amdhsa_reserve_vcc 1
		.amdhsa_float_round_mode_32 0
		.amdhsa_float_round_mode_16_64 0
		.amdhsa_float_denorm_mode_32 3
		.amdhsa_float_denorm_mode_16_64 3
		.amdhsa_dx10_clamp 1
		.amdhsa_ieee_mode 1
		.amdhsa_fp16_overflow 0
		.amdhsa_tg_split 0
		.amdhsa_exception_fp_ieee_invalid_op 0
		.amdhsa_exception_fp_denorm_src 0
		.amdhsa_exception_fp_ieee_div_zero 0
		.amdhsa_exception_fp_ieee_overflow 0
		.amdhsa_exception_fp_ieee_underflow 0
		.amdhsa_exception_fp_ieee_inexact 0
		.amdhsa_exception_int_div_zero 0
	.end_amdhsa_kernel

; __global__ void __launch_bounds__(512, 2) fwd_kernel(Params p) {
;     extern __shared__ __attribute__((aligned(16))) unsigned char smem[];
amdhsa.kernels:
  - .agpr_count:     0
    .args:
      - .offset:         0
        .size:           200
        .value_kind:     by_value
      - .offset:         200
        .size:           4
        .value_kind:     hidden_block_count_x
      - .offset:         204
        .size:           4
        .value_kind:     hidden_block_count_y
      - .offset:         208
        .size:           4
        .value_kind:     hidden_block_count_z
      - .offset:         212
        .size:           2
        .value_kind:     hidden_group_size_x
      - .offset:         214
        .size:           2
        .value_kind:     hidden_group_size_y
      - .offset:         216
        .size:           2
        .value_kind:     hidden_group_size_z
      - .offset:         218
        .size:           2
        .value_kind:     hidden_remainder_x
      - .offset:         220
        .size:           2
        .value_kind:     hidden_remainder_y
      - .offset:         222
        .size:           2
        .value_kind:     hidden_remainder_z
      - .offset:         240
        .size:           8
        .value_kind:     hidden_global_offset_x
      - .offset:         248
        .size:           8
        .value_kind:     hidden_global_offset_y
      - .offset:         256
        .size:           8
        .value_kind:     hidden_global_offset_z
      - .offset:         264
        .size:           2
        .value_kind:     hidden_grid_dims
      - .offset:         288
        .size:           8
        .value_kind:     hidden_multigrid_sync_arg
      - .offset:         320
        .size:           4
        .value_kind:     hidden_dynamic_lds_size
    .group_segment_fixed_size: 0
    .kernarg_segment_align: 8
    .kernarg_segment_size: 456
    .language:       OpenCL C
    .language_version:
      - 2
      - 0
    .max_flat_workgroup_size: 512
    .name:           _Z10fwd_kernel6Params
    .private_segment_fixed_size: 0
    .sgpr_count:     104
    .sgpr_spill_count: 52
    .symbol:         _Z10fwd_kernel6Params.kd
    .uniform_work_group_size: 1
    .uses_dynamic_stack: false
    .vgpr_count:     256
    .vgpr_spill_count: 0
    .wavefront_size: 64
